# plus phase-0 weight conversion: the 32 per-item RMSNorm gain loads issued together instead of one load-wait per element
# speedup vs baseline: 1.0219x; 1.0050x over previous
.LBB0_572:
	s_waitcnt vmcnt(0)
	v_mul_f32_e32 v0, v78, v127
	v_add_u32_e32 v6, s27, v48
	ds_write_b32 v6, v0
	s_waitcnt lgkmcnt(0)
	v_add_u32_e32 v49, s27, v11
	ds_read2_b32 v[6:7], v49 offset1:33
	ds_read2_b32 v[8:9], v49 offset0:66 offset1:99
	ds_read2_b32 v[50:51], v49 offset0:132 offset1:165
	ds_read2_b32 v[52:53], v49 offset0:198 offset1:231
	s_lshl_b64 s[2:3], s[20:21], 1
	s_add_u32 s2, s37, s2
	s_waitcnt lgkmcnt(3)
	v_cvt_pk_bf16_f32 v6, v6, v7
	s_waitcnt lgkmcnt(2)
	v_cvt_pk_bf16_f32 v7, v8, v9
	s_waitcnt lgkmcnt(1)
	v_cvt_pk_bf16_f32 v8, v50, v51
	v_or_b32_e32 v50, s5, v10
	s_addc_u32 s3, s40, s3
	v_lshlrev_b32_e32 v0, 1, v4
	v_ashrrev_i32_e32 v51, 31, v50
	v_lshl_add_u64 v[54:55], s[2:3], 0, v[0:1]
	v_lshlrev_b64 v[50:51], 11, v[50:51]
	s_waitcnt lgkmcnt(0)
	v_cvt_pk_bf16_f32 v9, v52, v53
	v_lshl_add_u64 v[50:51], v[54:55], 0, v[50:51]
	flat_store_dwordx4 v[50:51], v[6:9]
	v_add_u32_e32 v0, s27, v13
	ds_read2_b32 v[6:7], v0 offset1:33
	ds_read2_b32 v[8:9], v0 offset0:66 offset1:99
	ds_read2_b32 v[50:51], v0 offset0:132 offset1:165
	ds_read2_b32 v[52:53], v0 offset0:198 offset1:231
	v_add_u32_e32 v0, s27, v15
	s_waitcnt lgkmcnt(0)
	v_cvt_pk_bf16_f32 v6, v6, v7
	v_cvt_pk_bf16_f32 v7, v8, v9
	v_cvt_pk_bf16_f32 v8, v50, v51
	v_or_b32_e32 v50, s5, v12
	v_ashrrev_i32_e32 v51, 31, v50
	v_lshlrev_b64 v[50:51], 11, v[50:51]
	v_cvt_pk_bf16_f32 v9, v52, v53
	v_lshl_add_u64 v[50:51], v[54:55], 0, v[50:51]
	flat_store_dwordx4 v[50:51], v[6:9]
	ds_read2_b32 v[6:7], v0 offset1:33
	ds_read2_b32 v[8:9], v0 offset0:66 offset1:99
	ds_read2_b32 v[50:51], v0 offset0:132 offset1:165
	ds_read2_b32 v[52:53], v0 offset0:198 offset1:231
	v_add_u32_e32 v0, s27, v17
	s_waitcnt lgkmcnt(0)
	v_cvt_pk_bf16_f32 v6, v6, v7
	v_cvt_pk_bf16_f32 v7, v8, v9
	v_cvt_pk_bf16_f32 v8, v50, v51
	v_or_b32_e32 v50, s5, v14
	v_ashrrev_i32_e32 v51, 31, v50
	v_lshlrev_b64 v[50:51], 11, v[50:51]
	v_cvt_pk_bf16_f32 v9, v52, v53
	v_lshl_add_u64 v[50:51], v[54:55], 0, v[50:51]
	flat_store_dwordx4 v[50:51], v[6:9]
	ds_read2_b32 v[6:7], v0 offset1:33
	ds_read2_b32 v[8:9], v0 offset0:66 offset1:99
	ds_read2_b32 v[50:51], v0 offset0:132 offset1:165
	ds_read2_b32 v[52:53], v0 offset0:198 offset1:231
	s_waitcnt lgkmcnt(0)
	v_cvt_pk_bf16_f32 v6, v6, v7
	v_cvt_pk_bf16_f32 v7, v8, v9
	v_cvt_pk_bf16_f32 v8, v50, v51
	v_or_b32_e32 v50, s5, v16
	v_ashrrev_i32_e32 v51, 31, v50
	v_lshlrev_b64 v[50:51], 11, v[50:51]
	v_cvt_pk_bf16_f32 v9, v52, v53
	v_lshl_add_u64 v[50:51], v[54:55], 0, v[50:51]
	flat_store_dwordx4 v[50:51], v[6:9]
	s_waitcnt lgkmcnt(0)

.LBB0_580:
	s_andn2_b64 vcc, exec, s[2:3]
	s_cbranch_vccnz .LBB0_647
	s_mov_b32 s2, 24
	s_ashr_i32 s3, s2, 31
	s_lshl_b64 s[2:3], s[2:3], 3
	s_add_u32 s2, s0, s2
	s_addc_u32 s3, s1, s3
	s_load_dwordx2 s[38:39], s[2:3], 0x0
	s_mov_b32 s2, 25
	s_ashr_i32 s3, s2, 31
	s_lshl_b64 s[2:3], s[2:3], 3
	s_add_u32 s2, s0, s2
	s_addc_u32 s3, s1, s3
	s_load_dwordx2 s[42:43], s[2:3], 0x0
	s_mov_b32 s2, 23
	s_ashr_i32 s3, s2, 31
	s_lshl_b64 s[2:3], s[2:3], 3
	s_add_u32 s2, s0, s2
	s_addc_u32 s3, s1, s3
	s_load_dwordx2 s[2:3], s[2:3], 0x0
	s_lshl_b32 s6, s4, 10
	s_ashr_i32 s7, s6, 31
	s_lshl_b64 s[6:7], s[6:7], 2
	s_waitcnt lgkmcnt(0)
	s_add_u32 s6, s2, s6
	s_addc_u32 s7, s3, s7
	s_add_i32 s10, s41, 0xe600
	s_and_b32 s11, s10, 0xffff
	s_mul_i32 s11, s11, 0xba2f
	s_lshr_b32 s20, s11, 23
	s_mul_i32 s11, s20, 0xb0
	s_sub_i32 s21, s10, s11
	s_and_b32 s44, s21, 0xffff
	s_lshl_b32 s10, s44, 5
	s_lshl_b32 s11, s20, 6
	s_and_b32 s45, s10, 0x60
	s_bitcmp0_b32 s21, 2
	s_cselect_b32 s21, s39, s43
	s_cselect_b32 s42, s38, s42
	s_lshl_b64 s[38:39], s[24:25], 2
	s_add_u32 s38, s42, s38
	s_addc_u32 s39, s21, s39
	s_lshl_b32 s21, s44, 4
	s_and_b32 s21, s21, 0xf80
	s_or_b32 s21, s21, s45
	v_or_b32_e32 v0, s21, v3
	v_or_b32_e32 v8, s11, v2
	v_lshlrev_b32_e32 v0, 2, v0
	v_lshl_add_u64 v[6:7], s[38:39], 0, v[0:1]
	v_mul_u32_u24_e32 v0, 0x2c00, v8
	v_lshl_add_u64 v[6:7], v[6:7], 0, v[0:1]
	s_movk_i32 s21, 0x5000
	v_add_co_u32_e32 v8, vcc, s21, v6
	s_mov_b32 s21, 0xb000
	s_nop 0
	v_addc_co_u32_e32 v9, vcc, 0, v7, vcc
	v_add_co_u32_e32 v50, vcc, s21, v6
	s_mov_b32 s21, 0x16000
	s_nop 0
	v_addc_co_u32_e32 v51, vcc, 0, v7, vcc
	v_add_co_u32_e32 v52, vcc, s48, v6
	s_lshl_b32 s20, s20, 8
	s_nop 0
	v_addc_co_u32_e32 v53, vcc, 0, v7, vcc
	v_add_co_u32_e32 v54, vcc, s21, v6
	s_mov_b32 s21, 0x1b000
	s_nop 0
	v_addc_co_u32_e32 v55, vcc, 0, v7, vcc
	v_add_co_u32_e32 v56, vcc, s21, v6
	s_mov_b32 s21, 0x21000
	s_nop 0
	v_addc_co_u32_e32 v57, vcc, 0, v7, vcc
	v_add_co_u32_e32 v58, vcc, s21, v6
	s_mov_b32 s21, 0x26000
	s_nop 0
	v_addc_co_u32_e32 v59, vcc, 0, v7, vcc
	v_add_co_u32_e32 v60, vcc, s21, v6
	s_mov_b32 s21, 0x2c000
	s_nop 0
	v_addc_co_u32_e32 v61, vcc, 0, v7, vcc
	global_load_dword v78, v[6:7], off
	global_load_dword v77, v[8:9], off offset:2048
	global_load_dword v76, v[50:51], off
	global_load_dword v75, v[52:53], off offset:2048
	global_load_dword v74, v[54:55], off
	global_load_dword v72, v[56:57], off offset:2048
	global_load_dword v70, v[58:59], off
	global_load_dword v68, v[60:61], off offset:2048
	v_add_co_u32_e32 v8, vcc, s21, v6
	s_mov_b32 s21, 0x31000
	s_nop 0
	v_addc_co_u32_e32 v9, vcc, 0, v7, vcc
	v_add_co_u32_e32 v50, vcc, s21, v6
	s_mov_b32 s21, 0x37000
	s_nop 0
	v_addc_co_u32_e32 v51, vcc, 0, v7, vcc
	v_add_co_u32_e32 v52, vcc, s21, v6
	s_mov_b32 s21, 0x3c000
	s_nop 0
	v_addc_co_u32_e32 v53, vcc, 0, v7, vcc
	v_add_co_u32_e32 v54, vcc, s21, v6
	s_mov_b32 s21, 0x42000
	s_nop 0
	v_addc_co_u32_e32 v55, vcc, 0, v7, vcc
	v_add_co_u32_e32 v56, vcc, s21, v6
	s_mov_b32 s21, 0x47000
	s_nop 0
	v_addc_co_u32_e32 v57, vcc, 0, v7, vcc
	v_add_co_u32_e32 v58, vcc, s21, v6
	s_mov_b32 s21, 0x4d000
	s_nop 0
	v_addc_co_u32_e32 v59, vcc, 0, v7, vcc
	v_add_co_u32_e32 v60, vcc, s21, v6
	s_mov_b32 s21, 0x52000
	s_nop 0
	v_addc_co_u32_e32 v61, vcc, 0, v7, vcc
	v_add_co_u32_e32 v80, vcc, s21, v6
	s_mov_b32 s21, 0x58000
	s_nop 0
	v_addc_co_u32_e32 v81, vcc, 0, v7, vcc
	global_load_dword v73, v[8:9], off
	global_load_dword v71, v[50:51], off offset:2048
	global_load_dword v69, v[52:53], off
	global_load_dword v67, v[54:55], off offset:2048
	global_load_dword v66, v[56:57], off
	global_load_dword v64, v[58:59], off offset:2048
	global_load_dword v62, v[60:61], off
	s_nop 0
	global_load_dword v60, v[80:81], off offset:2048
	v_add_co_u32_e32 v8, vcc, s21, v6
	s_mov_b32 s21, 0x5d000
	s_nop 0
	v_addc_co_u32_e32 v9, vcc, 0, v7, vcc
	v_add_co_u32_e32 v50, vcc, s21, v6
	s_mov_b32 s21, 0x63000
	s_nop 0
	v_addc_co_u32_e32 v51, vcc, 0, v7, vcc
	v_add_co_u32_e32 v52, vcc, s21, v6
	s_mov_b32 s21, 0x68000
	s_nop 0
	v_addc_co_u32_e32 v53, vcc, 0, v7, vcc
	v_add_co_u32_e32 v54, vcc, s21, v6
	s_mov_b32 s21, 0x6e000
	s_nop 0
	v_addc_co_u32_e32 v55, vcc, 0, v7, vcc
	v_add_co_u32_e32 v56, vcc, s21, v6
	s_mov_b32 s21, 0x73000
	s_nop 0
	v_addc_co_u32_e32 v57, vcc, 0, v7, vcc
	v_add_co_u32_e32 v80, vcc, s21, v6
	s_mov_b32 s21, 0x79000
	s_nop 0
	v_addc_co_u32_e32 v81, vcc, 0, v7, vcc
	v_add_co_u32_e32 v82, vcc, s21, v6
	s_mov_b32 s21, 0x7e000
	s_nop 0
	v_addc_co_u32_e32 v83, vcc, 0, v7, vcc
	v_add_co_u32_e32 v84, vcc, s21, v6
	s_mov_b32 s21, 0x84000
	s_nop 0
	v_addc_co_u32_e32 v85, vcc, 0, v7, vcc
	global_load_dword v65, v[8:9], off
	global_load_dword v63, v[50:51], off offset:2048
	global_load_dword v61, v[52:53], off
	global_load_dword v59, v[54:55], off offset:2048
	s_nop 0
	global_load_dword v57, v[56:57], off
	s_nop 0
	global_load_dword v55, v[80:81], off offset:2048
	global_load_dword v53, v[82:83], off
	global_load_dword v52, v[84:85], off offset:2048
	v_add_co_u32_e32 v8, vcc, s21, v6
	s_mov_b32 s21, 0x89000
	s_nop 0
	v_addc_co_u32_e32 v9, vcc, 0, v7, vcc
	v_add_co_u32_e32 v50, vcc, s21, v6
	s_mov_b32 s21, 0x8f000
	s_nop 0
	v_addc_co_u32_e32 v51, vcc, 0, v7, vcc
	v_add_co_u32_e32 v80, vcc, s21, v6
	s_mov_b32 s21, 0x94000
	s_nop 0
	v_addc_co_u32_e32 v81, vcc, 0, v7, vcc
	v_add_co_u32_e32 v82, vcc, s21, v6
	s_mov_b32 s21, 0x9a000
	s_nop 0
	v_addc_co_u32_e32 v83, vcc, 0, v7, vcc
	v_add_co_u32_e32 v84, vcc, s21, v6
	s_mov_b32 s21, 0x9f000
	s_nop 0
	v_addc_co_u32_e32 v85, vcc, 0, v7, vcc
	v_add_co_u32_e32 v86, vcc, s21, v6
	s_mov_b32 s21, 0xa5000
	s_nop 0
	v_addc_co_u32_e32 v87, vcc, 0, v7, vcc
	v_add_co_u32_e32 v88, vcc, s21, v6
	s_mov_b32 s21, 0xaa000
	s_nop 0
	v_addc_co_u32_e32 v89, vcc, 0, v7, vcc
	v_add_co_u32_e32 v6, vcc, s21, v6
	s_add_u32 s20, s6, s20
	s_nop 0
	v_addc_co_u32_e32 v7, vcc, 0, v7, vcc
	global_load_dword v58, v[8:9], off
	global_load_dword v56, v[50:51], off offset:2048
	global_load_dword v54, v[80:81], off
	s_nop 0
	global_load_dword v51, v[82:83], off offset:2048
	global_load_dword v50, v[84:85], off
	global_load_dword v49, v[86:87], off offset:2048
	global_load_dword v9, v[88:89], off
	global_load_dword v8, v[6:7], off offset:2048
	s_addc_u32 s21, s7, 0
	v_lshlrev_b32_e32 v0, 2, v2
	s_cmp_lg_u64 s[2:3], 0
	s_cselect_b64 s[6:7], -1, 0
	s_cmp_eq_u64 s[2:3], 0
	v_lshl_add_u64 v[6:7], s[20:21], 0, v[0:1]
	s_cbranch_scc1 .LBB0_583
	global_load_dword v96, v[6:7], off offset:0
	global_load_dword v97, v[6:7], off offset:8
	global_load_dword v98, v[6:7], off offset:16
	global_load_dword v99, v[6:7], off offset:24
	global_load_dword v100, v[6:7], off offset:32
	global_load_dword v101, v[6:7], off offset:40
	global_load_dword v102, v[6:7], off offset:48
	global_load_dword v103, v[6:7], off offset:56
	global_load_dword v104, v[6:7], off offset:64
	global_load_dword v105, v[6:7], off offset:72
	global_load_dword v106, v[6:7], off offset:80
	global_load_dword v107, v[6:7], off offset:88
	global_load_dword v108, v[6:7], off offset:96
	global_load_dword v109, v[6:7], off offset:104
	global_load_dword v110, v[6:7], off offset:112
	global_load_dword v111, v[6:7], off offset:120
	global_load_dword v112, v[6:7], off offset:128
	global_load_dword v113, v[6:7], off offset:136
	global_load_dword v114, v[6:7], off offset:144
	global_load_dword v115, v[6:7], off offset:152
	global_load_dword v116, v[6:7], off offset:160
	global_load_dword v117, v[6:7], off offset:168
	global_load_dword v118, v[6:7], off offset:176
	global_load_dword v119, v[6:7], off offset:184
	global_load_dword v120, v[6:7], off offset:192
	global_load_dword v121, v[6:7], off offset:200
	global_load_dword v122, v[6:7], off offset:208
	global_load_dword v123, v[6:7], off offset:216
	global_load_dword v124, v[6:7], off offset:224
	global_load_dword v125, v[6:7], off offset:232
	global_load_dword v126, v[6:7], off offset:240
	global_load_dword v127, v[6:7], off offset:248
	s_branch .LBB0_584
.LBB0_583:
	v_mov_b32_e32 v96, 1.0
	v_mov_b32_e32 v97, 1.0
	v_mov_b32_e32 v98, 1.0
	v_mov_b32_e32 v99, 1.0
	v_mov_b32_e32 v100, 1.0
	v_mov_b32_e32 v101, 1.0
	v_mov_b32_e32 v102, 1.0
	v_mov_b32_e32 v103, 1.0
	v_mov_b32_e32 v104, 1.0
	v_mov_b32_e32 v105, 1.0
	v_mov_b32_e32 v106, 1.0
	v_mov_b32_e32 v107, 1.0
	v_mov_b32_e32 v108, 1.0
	v_mov_b32_e32 v109, 1.0
	v_mov_b32_e32 v110, 1.0
	v_mov_b32_e32 v111, 1.0
	v_mov_b32_e32 v112, 1.0
	v_mov_b32_e32 v113, 1.0
	v_mov_b32_e32 v114, 1.0
	v_mov_b32_e32 v115, 1.0
	v_mov_b32_e32 v116, 1.0
	v_mov_b32_e32 v117, 1.0
	v_mov_b32_e32 v118, 1.0
	v_mov_b32_e32 v119, 1.0
	v_mov_b32_e32 v120, 1.0
	v_mov_b32_e32 v121, 1.0
	v_mov_b32_e32 v122, 1.0
	v_mov_b32_e32 v123, 1.0
	v_mov_b32_e32 v124, 1.0
	v_mov_b32_e32 v125, 1.0
	v_mov_b32_e32 v126, 1.0
	v_mov_b32_e32 v127, 1.0
.LBB0_584:
	v_cndmask_b32_e64 v79, 0, 1, s[6:7]
	s_waitcnt vmcnt(0)
	v_mul_f32_e32 v78, v78, v96
	v_cmp_ne_u32_e64 s[38:39], 1, v79
	s_andn2_b64 vcc, exec, s[6:7]
	ds_write_b32 v5, v78
	s_cbranch_vccnz .LBB0_586
	s_nop 0
.LBB0_586:
	s_waitcnt vmcnt(0)
	v_mul_f32_e32 v77, v77, v97
	v_add_u32_e32 v78, s27, v18
	s_and_b64 vcc, exec, s[38:39]
	ds_write_b32 v78, v77
	s_cbranch_vccnz .LBB0_588
	s_nop 0
.LBB0_588:
	s_waitcnt vmcnt(0)
	v_mul_f32_e32 v76, v76, v98
	v_add_u32_e32 v77, s27, v19
	s_and_b64 vcc, exec, s[38:39]
	ds_write_b32 v77, v76
	s_cbranch_vccnz .LBB0_590
	s_nop 0
.LBB0_590:
	s_waitcnt vmcnt(0)
	v_mul_f32_e32 v75, v75, v99
	v_add_u32_e32 v76, s27, v20
	s_and_b64 vcc, exec, s[38:39]
	ds_write_b32 v76, v75
	s_cbranch_vccnz .LBB0_592
	s_nop 0
.LBB0_592:
	s_waitcnt vmcnt(0)
	v_mul_f32_e32 v74, v74, v100
	v_add_u32_e32 v75, s27, v21
	s_and_b64 vcc, exec, s[38:39]
	ds_write_b32 v75, v74
	s_cbranch_vccnz .LBB0_594
	s_nop 0
.LBB0_594:
	s_waitcnt vmcnt(0)
	v_mul_f32_e32 v72, v72, v101
	v_add_u32_e32 v74, s27, v22
	s_and_b64 vcc, exec, s[38:39]
	ds_write_b32 v74, v72
	s_cbranch_vccnz .LBB0_596
	s_nop 0
.LBB0_596:
	s_waitcnt vmcnt(0)
	v_mul_f32_e32 v70, v70, v102
	v_add_u32_e32 v72, s27, v23
	s_and_b64 vcc, exec, s[38:39]
	ds_write_b32 v72, v70
	s_cbranch_vccnz .LBB0_598
	s_nop 0
.LBB0_598:
	s_waitcnt vmcnt(0)
	v_mul_f32_e32 v68, v68, v103
	v_add_u32_e32 v70, s27, v24
	s_and_b64 vcc, exec, s[38:39]
	ds_write_b32 v70, v68
	s_cbranch_vccnz .LBB0_600
	s_nop 0
.LBB0_600:
	s_waitcnt vmcnt(0)
	v_mul_f32_e32 v68, v73, v104
	v_add_u32_e32 v70, s27, v25
	s_and_b64 vcc, exec, s[38:39]
	ds_write_b32 v70, v68
	s_cbranch_vccnz .LBB0_602
	s_nop 0
.LBB0_602:
	s_waitcnt vmcnt(0)
	v_mul_f32_e32 v68, v71, v105
	v_add_u32_e32 v70, s27, v26
	s_and_b64 vcc, exec, s[38:39]
	ds_write_b32 v70, v68
	s_cbranch_vccnz .LBB0_604
	s_nop 0
.LBB0_604:
	s_waitcnt vmcnt(0)
	v_mul_f32_e32 v68, v69, v106
	v_add_u32_e32 v69, s27, v27
	s_and_b64 vcc, exec, s[38:39]
	ds_write_b32 v69, v68
	s_cbranch_vccnz .LBB0_606
	s_nop 0
.LBB0_606:
	s_waitcnt vmcnt(0)
	v_mul_f32_e32 v67, v67, v107
	v_add_u32_e32 v68, s27, v28
	s_and_b64 vcc, exec, s[38:39]
	ds_write_b32 v68, v67
	s_cbranch_vccnz .LBB0_608
	s_nop 0
.LBB0_608:
	s_waitcnt vmcnt(0)
	v_mul_f32_e32 v66, v66, v108
	v_add_u32_e32 v67, s27, v29
	s_and_b64 vcc, exec, s[38:39]
	ds_write_b32 v67, v66
	s_cbranch_vccnz .LBB0_610
	s_nop 0
.LBB0_610:
	s_waitcnt vmcnt(0)
	v_mul_f32_e32 v64, v64, v109
	v_add_u32_e32 v66, s27, v30
	s_and_b64 vcc, exec, s[38:39]
	ds_write_b32 v66, v64
	s_cbranch_vccnz .LBB0_612
	s_nop 0
.LBB0_612:
	s_waitcnt vmcnt(0)
	v_mul_f32_e32 v62, v62, v110
	v_add_u32_e32 v64, s27, v31
	s_and_b64 vcc, exec, s[38:39]
	ds_write_b32 v64, v62
	s_cbranch_vccnz .LBB0_614
	s_nop 0
.LBB0_614:
	s_waitcnt vmcnt(0)
	v_mul_f32_e32 v60, v60, v111
	v_add_u32_e32 v62, s27, v32
	s_and_b64 vcc, exec, s[38:39]
	ds_write_b32 v62, v60
	s_cbranch_vccnz .LBB0_616
	s_nop 0
.LBB0_616:
	s_waitcnt vmcnt(0)
	v_mul_f32_e32 v60, v65, v112
	v_add_u32_e32 v62, s27, v33
	s_and_b64 vcc, exec, s[38:39]
	ds_write_b32 v62, v60
	s_cbranch_vccnz .LBB0_618
	s_nop 0
.LBB0_618:
	s_waitcnt vmcnt(0)
	v_mul_f32_e32 v60, v63, v113
	v_add_u32_e32 v62, s27, v34
	s_and_b64 vcc, exec, s[38:39]
	ds_write_b32 v62, v60
	s_cbranch_vccnz .LBB0_620
	s_nop 0
.LBB0_620:
	s_waitcnt vmcnt(0)
	v_mul_f32_e32 v60, v61, v114
	v_add_u32_e32 v61, s27, v35
	s_and_b64 vcc, exec, s[38:39]
	ds_write_b32 v61, v60
	s_cbranch_vccnz .LBB0_622
	s_nop 0
.LBB0_622:
	s_waitcnt vmcnt(0)
	v_mul_f32_e32 v59, v59, v115
	v_add_u32_e32 v60, s27, v36
	s_and_b64 vcc, exec, s[38:39]
	ds_write_b32 v60, v59
	s_cbranch_vccnz .LBB0_624
	s_nop 0
.LBB0_624:
	s_waitcnt vmcnt(0)
	v_mul_f32_e32 v57, v57, v116
	v_add_u32_e32 v59, s27, v37
	s_and_b64 vcc, exec, s[38:39]
	ds_write_b32 v59, v57
	s_cbranch_vccnz .LBB0_626
	s_nop 0
.LBB0_626:
	s_waitcnt vmcnt(0)
	v_mul_f32_e32 v55, v55, v117
	v_add_u32_e32 v57, s27, v38
	s_and_b64 vcc, exec, s[38:39]
	ds_write_b32 v57, v55
	s_cbranch_vccnz .LBB0_628
	s_nop 0
.LBB0_628:
	s_waitcnt vmcnt(0)
	v_mul_f32_e32 v53, v53, v118
	v_add_u32_e32 v55, s27, v39
	s_and_b64 vcc, exec, s[38:39]
	ds_write_b32 v55, v53
	s_cbranch_vccnz .LBB0_630
	s_nop 0
.LBB0_630:
	s_waitcnt vmcnt(0)
	v_mul_f32_e32 v52, v52, v119
	v_add_u32_e32 v53, s27, v40
	s_and_b64 vcc, exec, s[38:39]
	ds_write_b32 v53, v52
	s_cbranch_vccnz .LBB0_632
	s_nop 0
.LBB0_632:
	s_waitcnt vmcnt(0)
	v_mul_f32_e32 v52, v58, v120
	v_add_u32_e32 v53, s27, v41
	s_and_b64 vcc, exec, s[38:39]
	ds_write_b32 v53, v52
	s_cbranch_vccnz .LBB0_634
	s_nop 0
.LBB0_634:
	s_waitcnt vmcnt(0)
	v_mul_f32_e32 v52, v56, v121
	v_add_u32_e32 v53, s27, v42
	s_and_b64 vcc, exec, s[38:39]
	ds_write_b32 v53, v52
	s_cbranch_vccnz .LBB0_636
	s_nop 0
.LBB0_636:
	s_waitcnt vmcnt(0)
	v_mul_f32_e32 v52, v54, v122
	v_add_u32_e32 v53, s27, v43
	s_and_b64 vcc, exec, s[38:39]
	ds_write_b32 v53, v52
	s_cbranch_vccnz .LBB0_638
	s_nop 0
.LBB0_638:
	s_waitcnt vmcnt(0)
	v_mul_f32_e32 v51, v51, v123
	v_add_u32_e32 v52, s27, v44
	s_and_b64 vcc, exec, s[38:39]
	ds_write_b32 v52, v51
	s_cbranch_vccnz .LBB0_640
	s_nop 0
.LBB0_640:
	s_waitcnt vmcnt(0)
	v_mul_f32_e32 v50, v50, v124
	v_add_u32_e32 v51, s27, v45
	s_and_b64 vcc, exec, s[38:39]
	ds_write_b32 v51, v50
	s_cbranch_vccnz .LBB0_642
	s_nop 0
.LBB0_642:
	s_waitcnt vmcnt(0)
	v_mul_f32_e32 v49, v49, v125
	v_add_u32_e32 v50, s27, v46
	s_and_b64 vcc, exec, s[38:39]
	ds_write_b32 v50, v49
	s_cbranch_vccnz .LBB0_644
	s_nop 0
.LBB0_644:
	s_waitcnt vmcnt(0)
	v_mul_f32_e32 v9, v9, v126
	v_add_u32_e32 v49, s27, v47
	s_and_b64 vcc, exec, s[38:39]
	ds_write_b32 v49, v9
	s_cbranch_vccnz .LBB0_646
	s_nop 0
.LBB0_646:
	s_lshl_b32 s2, s11, 1
	s_waitcnt vmcnt(0)
	v_mul_f32_e32 v0, v8, v127
	v_add_u32_e32 v6, s27, v48
	s_add_u32 s2, s37, s2
	ds_write_b32 v6, v0
	s_addc_u32 s3, s40, 0
	v_lshlrev_b32_e32 v0, 1, v4
	s_waitcnt lgkmcnt(0)
	v_lshl_add_u64 v[6:7], s[2:3], 0, v[0:1]
	v_add_u32_e32 v0, s27, v11
	ds_read2_b32 v[8:9], v0 offset1:33
	ds_read2_b32 v[50:51], v0 offset0:66 offset1:99
	ds_read2_b32 v[52:53], v0 offset0:132 offset1:165
	ds_read2_b32 v[54:55], v0 offset0:198 offset1:231
	s_mov_b64 s[2:3], 0x1a00000
	v_or_b32_e32 v0, s10, v10
	v_lshl_add_u64 v[56:57], v[6:7], 0, s[2:3]
	v_lshlrev_b32_e32 v0, 11, v0
	s_waitcnt lgkmcnt(3)
	v_cvt_pk_bf16_f32 v6, v8, v9
	s_waitcnt lgkmcnt(2)
	v_cvt_pk_bf16_f32 v7, v50, v51
	s_waitcnt lgkmcnt(1)
	v_cvt_pk_bf16_f32 v8, v52, v53
	s_waitcnt lgkmcnt(0)
	v_cvt_pk_bf16_f32 v9, v54, v55
	v_lshl_add_u64 v[50:51], v[56:57], 0, v[0:1]
	flat_store_dwordx4 v[50:51], v[6:9]
	v_add_u32_e32 v0, s27, v13
	ds_read2_b32 v[6:7], v0 offset1:33
	ds_read2_b32 v[8:9], v0 offset0:66 offset1:99
	ds_read2_b32 v[50:51], v0 offset0:132 offset1:165
	ds_read2_b32 v[52:53], v0 offset0:198 offset1:231
	v_or_b32_e32 v0, s10, v12
	v_lshlrev_b32_e32 v0, 11, v0
	s_waitcnt lgkmcnt(0)
	v_cvt_pk_bf16_f32 v6, v6, v7
	v_cvt_pk_bf16_f32 v7, v8, v9
	v_cvt_pk_bf16_f32 v8, v50, v51
	v_cvt_pk_bf16_f32 v9, v52, v53
	v_lshl_add_u64 v[50:51], v[56:57], 0, v[0:1]
	flat_store_dwordx4 v[50:51], v[6:9]
	v_add_u32_e32 v0, s27, v15
	ds_read2_b32 v[6:7], v0 offset1:33
	ds_read2_b32 v[8:9], v0 offset0:66 offset1:99
	ds_read2_b32 v[50:51], v0 offset0:132 offset1:165
	ds_read2_b32 v[52:53], v0 offset0:198 offset1:231
	v_or_b32_e32 v0, s10, v14
	v_lshlrev_b32_e32 v0, 11, v0
	s_waitcnt lgkmcnt(0)
	v_cvt_pk_bf16_f32 v6, v6, v7
	v_cvt_pk_bf16_f32 v7, v8, v9
	v_cvt_pk_bf16_f32 v8, v50, v51
	v_cvt_pk_bf16_f32 v9, v52, v53
	v_lshl_add_u64 v[50:51], v[56:57], 0, v[0:1]
	flat_store_dwordx4 v[50:51], v[6:9]
	v_add_u32_e32 v0, s27, v17
	ds_read2_b32 v[6:7], v0 offset1:33
	ds_read2_b32 v[8:9], v0 offset0:66 offset1:99
	ds_read2_b32 v[50:51], v0 offset0:132 offset1:165
	ds_read2_b32 v[52:53], v0 offset0:198 offset1:231
	v_or_b32_e32 v0, s10, v16
	v_lshlrev_b32_e32 v0, 11, v0
	s_waitcnt lgkmcnt(0)
	v_cvt_pk_bf16_f32 v6, v6, v7
	v_cvt_pk_bf16_f32 v7, v8, v9
	v_cvt_pk_bf16_f32 v8, v50, v51
	v_cvt_pk_bf16_f32 v9, v52, v53
	v_lshl_add_u64 v[50:51], v[56:57], 0, v[0:1]
	flat_store_dwordx4 v[50:51], v[6:9]
	s_waitcnt lgkmcnt(0)

.LBB0_738:
	s_or_b64 exec, exec, s[2:3]
	s_lshl_b32 s2, s4, 10
	s_ashr_i32 s3, s2, 31
	s_lshl_b64 s[2:3], s[2:3], 2
	s_add_u32 s2, s20, s2
	s_addc_u32 s3, s21, s3
	s_lshl_b32 s7, s6, 2
	s_add_u32 s10, s2, s7
	s_addc_u32 s11, s3, 0
	v_lshlrev_b32_e32 v0, 2, v2
	s_cmp_lg_u64 s[20:21], 0
	s_cselect_b64 s[2:3], -1, 0
	s_cmp_eq_u64 s[20:21], 0
	v_lshl_add_u64 v[6:7], s[10:11], 0, v[0:1]
	s_cbranch_scc1 .LBB0_740
	global_load_dword v96, v[6:7], off offset:0
	global_load_dword v97, v[6:7], off offset:8
	global_load_dword v98, v[6:7], off offset:16
	global_load_dword v99, v[6:7], off offset:24
	global_load_dword v100, v[6:7], off offset:32
	global_load_dword v101, v[6:7], off offset:40
	global_load_dword v102, v[6:7], off offset:48
	global_load_dword v103, v[6:7], off offset:56
	global_load_dword v104, v[6:7], off offset:64
	global_load_dword v105, v[6:7], off offset:72
	global_load_dword v106, v[6:7], off offset:80
	global_load_dword v107, v[6:7], off offset:88
	global_load_dword v108, v[6:7], off offset:96
	global_load_dword v109, v[6:7], off offset:104
	global_load_dword v110, v[6:7], off offset:112
	global_load_dword v111, v[6:7], off offset:120
	global_load_dword v112, v[6:7], off offset:128
	global_load_dword v113, v[6:7], off offset:136
	global_load_dword v114, v[6:7], off offset:144
	global_load_dword v115, v[6:7], off offset:152
	global_load_dword v116, v[6:7], off offset:160
	global_load_dword v117, v[6:7], off offset:168
	global_load_dword v118, v[6:7], off offset:176
	global_load_dword v119, v[6:7], off offset:184
	global_load_dword v120, v[6:7], off offset:192
	global_load_dword v121, v[6:7], off offset:200
	global_load_dword v122, v[6:7], off offset:208
	global_load_dword v123, v[6:7], off offset:216
	global_load_dword v124, v[6:7], off offset:224
	global_load_dword v125, v[6:7], off offset:232
	global_load_dword v126, v[6:7], off offset:240
	global_load_dword v127, v[6:7], off offset:248
	s_branch .LBB0_741

.LBB0_741:
	v_cndmask_b32_e64 v79, 0, 1, s[2:3]
	s_waitcnt vmcnt(0)
	v_mul_f32_e32 v9, v9, v96
	v_cmp_ne_u32_e64 s[38:39], 1, v79
	s_andn2_b64 vcc, exec, s[2:3]
	ds_write_b32 v5, v9
	s_cbranch_vccnz .LBB0_743
	s_nop 0
.LBB0_743:
	s_waitcnt vmcnt(0)
	v_mul_f32_e32 v8, v8, v97
	v_add_u32_e32 v9, s27, v18
	s_and_b64 vcc, exec, s[38:39]
	ds_write_b32 v9, v8
	s_cbranch_vccnz .LBB0_745
	s_nop 0
.LBB0_745:
	s_waitcnt vmcnt(0)
	v_mul_f32_e32 v8, v50, v98
	v_add_u32_e32 v9, s27, v19
	s_and_b64 vcc, exec, s[38:39]
	ds_write_b32 v9, v8
	s_cbranch_vccnz .LBB0_747
	s_nop 0
.LBB0_747:
	s_waitcnt vmcnt(0)
	v_mul_f32_e32 v8, v49, v99
	v_add_u32_e32 v9, s27, v20
	s_and_b64 vcc, exec, s[38:39]
	ds_write_b32 v9, v8
	s_cbranch_vccnz .LBB0_749
	s_nop 0
.LBB0_749:
	s_waitcnt vmcnt(0)
	v_mul_f32_e32 v8, v52, v100
	v_add_u32_e32 v9, s27, v21
	s_and_b64 vcc, exec, s[38:39]
	ds_write_b32 v9, v8
	s_cbranch_vccnz .LBB0_751
	s_nop 0
.LBB0_751:
	s_waitcnt vmcnt(0)
	v_mul_f32_e32 v8, v51, v101
	v_add_u32_e32 v9, s27, v22
	s_and_b64 vcc, exec, s[38:39]
	ds_write_b32 v9, v8
	s_cbranch_vccnz .LBB0_753
	s_nop 0
.LBB0_753:
	s_waitcnt vmcnt(0)
	v_mul_f32_e32 v8, v54, v102
	v_add_u32_e32 v9, s27, v23
	s_and_b64 vcc, exec, s[38:39]
	ds_write_b32 v9, v8
	s_cbranch_vccnz .LBB0_755
	s_nop 0
.LBB0_755:
	s_waitcnt vmcnt(0)
	v_mul_f32_e32 v8, v53, v103
	v_add_u32_e32 v9, s27, v24
	s_and_b64 vcc, exec, s[38:39]
	ds_write_b32 v9, v8
	s_cbranch_vccnz .LBB0_757
	s_nop 0
.LBB0_757:
	s_waitcnt vmcnt(0)
	v_mul_f32_e32 v8, v56, v104
	v_add_u32_e32 v9, s27, v25
	s_and_b64 vcc, exec, s[38:39]
	ds_write_b32 v9, v8
	s_cbranch_vccnz .LBB0_759
	s_nop 0
.LBB0_759:
	s_waitcnt vmcnt(0)
	v_mul_f32_e32 v8, v55, v105
	v_add_u32_e32 v9, s27, v26
	s_and_b64 vcc, exec, s[38:39]
	ds_write_b32 v9, v8
	s_cbranch_vccnz .LBB0_761
	s_nop 0
.LBB0_761:
	s_waitcnt vmcnt(0)
	v_mul_f32_e32 v8, v58, v106
	v_add_u32_e32 v9, s27, v27
	s_and_b64 vcc, exec, s[38:39]
	ds_write_b32 v9, v8
	s_cbranch_vccnz .LBB0_763
	s_nop 0
.LBB0_763:
	s_waitcnt vmcnt(0)
	v_mul_f32_e32 v8, v57, v107
	v_add_u32_e32 v9, s27, v28
	s_and_b64 vcc, exec, s[38:39]
	ds_write_b32 v9, v8
	s_cbranch_vccnz .LBB0_765
	s_nop 0
.LBB0_765:
	s_waitcnt vmcnt(0)
	v_mul_f32_e32 v8, v60, v108
	v_add_u32_e32 v9, s27, v29
	s_and_b64 vcc, exec, s[38:39]
	ds_write_b32 v9, v8
	s_cbranch_vccnz .LBB0_767
	s_nop 0
.LBB0_767:
	s_waitcnt vmcnt(0)
	v_mul_f32_e32 v8, v59, v109
	v_add_u32_e32 v9, s27, v30
	s_and_b64 vcc, exec, s[38:39]
	ds_write_b32 v9, v8
	s_cbranch_vccnz .LBB0_769
	s_nop 0
.LBB0_769:
	s_waitcnt vmcnt(0)
	v_mul_f32_e32 v8, v62, v110
	v_add_u32_e32 v9, s27, v31
	s_and_b64 vcc, exec, s[38:39]
	ds_write_b32 v9, v8
	s_cbranch_vccnz .LBB0_771
	s_nop 0
.LBB0_771:
	s_waitcnt vmcnt(0)
	v_mul_f32_e32 v8, v61, v111
	v_add_u32_e32 v9, s27, v32
	s_and_b64 vcc, exec, s[38:39]
	ds_write_b32 v9, v8
	s_cbranch_vccnz .LBB0_773
	s_nop 0
.LBB0_773:
	s_waitcnt vmcnt(0)
	v_mul_f32_e32 v8, v64, v112
	v_add_u32_e32 v9, s27, v33
	s_and_b64 vcc, exec, s[38:39]
	ds_write_b32 v9, v8
	s_cbranch_vccnz .LBB0_775
	s_nop 0
.LBB0_775:
	s_waitcnt vmcnt(0)
	v_mul_f32_e32 v8, v63, v113
	v_add_u32_e32 v9, s27, v34
	s_and_b64 vcc, exec, s[38:39]
	ds_write_b32 v9, v8
	s_cbranch_vccnz .LBB0_777
	s_nop 0
.LBB0_777:
	s_waitcnt vmcnt(0)
	v_mul_f32_e32 v8, v66, v114
	v_add_u32_e32 v9, s27, v35
	s_and_b64 vcc, exec, s[38:39]
	ds_write_b32 v9, v8
	s_cbranch_vccnz .LBB0_779
	s_nop 0
.LBB0_779:
	s_waitcnt vmcnt(0)
	v_mul_f32_e32 v8, v65, v115
	v_add_u32_e32 v9, s27, v36
	s_and_b64 vcc, exec, s[38:39]
	ds_write_b32 v9, v8
	s_cbranch_vccnz .LBB0_781
	s_nop 0
.LBB0_781:
	s_waitcnt vmcnt(0)
	v_mul_f32_e32 v8, v68, v116
	v_add_u32_e32 v9, s27, v37
	s_and_b64 vcc, exec, s[38:39]
	ds_write_b32 v9, v8
	s_cbranch_vccnz .LBB0_783
	s_nop 0
.LBB0_783:
	s_waitcnt vmcnt(0)
	v_mul_f32_e32 v8, v67, v117
	v_add_u32_e32 v9, s27, v38
	s_and_b64 vcc, exec, s[38:39]
	ds_write_b32 v9, v8
	s_cbranch_vccnz .LBB0_785
	s_nop 0
.LBB0_785:
	s_waitcnt vmcnt(0)
	v_mul_f32_e32 v8, v70, v118
	v_add_u32_e32 v9, s27, v39
	s_and_b64 vcc, exec, s[38:39]
	ds_write_b32 v9, v8
	s_cbranch_vccnz .LBB0_787
	s_nop 0
.LBB0_787:
	s_waitcnt vmcnt(0)
	v_mul_f32_e32 v8, v69, v119
	v_add_u32_e32 v9, s27, v40
	s_and_b64 vcc, exec, s[38:39]
	ds_write_b32 v9, v8
	s_cbranch_vccnz .LBB0_789
	s_nop 0
.LBB0_789:
	s_waitcnt vmcnt(0)
	v_mul_f32_e32 v8, v72, v120
	v_add_u32_e32 v9, s27, v41
	s_and_b64 vcc, exec, s[38:39]
	ds_write_b32 v9, v8
	s_cbranch_vccnz .LBB0_791
	s_nop 0
.LBB0_791:
	s_waitcnt vmcnt(0)
	v_mul_f32_e32 v8, v71, v121
	v_add_u32_e32 v9, s27, v42
	s_and_b64 vcc, exec, s[38:39]
	ds_write_b32 v9, v8
	s_cbranch_vccnz .LBB0_793
	s_nop 0
.LBB0_793:
	s_waitcnt vmcnt(0)
	v_mul_f32_e32 v8, v74, v122
	v_add_u32_e32 v9, s27, v43
	s_and_b64 vcc, exec, s[38:39]
	ds_write_b32 v9, v8
	s_cbranch_vccnz .LBB0_795
	s_nop 0
.LBB0_795:
	s_waitcnt vmcnt(0)
	v_mul_f32_e32 v8, v73, v123
	v_add_u32_e32 v9, s27, v44
	s_and_b64 vcc, exec, s[38:39]
	ds_write_b32 v9, v8
	s_cbranch_vccnz .LBB0_797
	s_nop 0
.LBB0_797:
	s_waitcnt vmcnt(0)
	v_mul_f32_e32 v8, v76, v124
	v_add_u32_e32 v9, s27, v45
	s_and_b64 vcc, exec, s[38:39]
	ds_write_b32 v9, v8
	s_cbranch_vccnz .LBB0_799
	s_nop 0
.LBB0_799:
	s_waitcnt vmcnt(0)
	v_mul_f32_e32 v8, v75, v125
	v_add_u32_e32 v9, s27, v46
	s_and_b64 vcc, exec, s[38:39]
	ds_write_b32 v9, v8
	s_cbranch_vccnz .LBB0_801
	s_nop 0
.LBB0_801:
	s_waitcnt vmcnt(0)
	v_mul_f32_e32 v8, v78, v126
	v_add_u32_e32 v9, s27, v47
	s_and_b64 vcc, exec, s[38:39]
	ds_write_b32 v9, v8
	s_cbranch_vccnz .LBB0_803
	s_nop 0
.LBB0_803:
	s_lshl_b32 s2, s6, 1
	s_waitcnt vmcnt(0)
	v_mul_f32_e32 v0, v77, v127
	v_add_u32_e32 v6, s27, v48
	s_add_u32 s2, s37, s2
	ds_write_b32 v6, v0
	s_addc_u32 s3, s40, 0
	v_lshlrev_b32_e32 v0, 1, v4
	s_waitcnt lgkmcnt(0)
	v_lshl_add_u64 v[6:7], s[2:3], 0, v[0:1]
	v_add_u32_e32 v0, s27, v11
	ds_read2_b32 v[8:9], v0 offset1:33
	ds_read2_b32 v[50:51], v0 offset0:66 offset1:99
	ds_read2_b32 v[52:53], v0 offset0:132 offset1:165
	ds_read2_b32 v[54:55], v0 offset0:198 offset1:231
	s_mov_b64 s[2:3], 0x1080000
	v_or_b32_e32 v0, s5, v10
	v_lshl_add_u64 v[56:57], v[6:7], 0, s[2:3]
	v_lshlrev_b32_e32 v0, 11, v0
	s_waitcnt lgkmcnt(3)
	v_cvt_pk_bf16_f32 v6, v8, v9
	s_waitcnt lgkmcnt(2)
	v_cvt_pk_bf16_f32 v7, v50, v51
	s_waitcnt lgkmcnt(1)
	v_cvt_pk_bf16_f32 v8, v52, v53
	s_waitcnt lgkmcnt(0)
	v_cvt_pk_bf16_f32 v9, v54, v55
	v_lshl_add_u64 v[50:51], v[56:57], 0, v[0:1]
	flat_store_dwordx4 v[50:51], v[6:9]
	v_add_u32_e32 v0, s27, v13
	ds_read2_b32 v[6:7], v0 offset1:33
	ds_read2_b32 v[8:9], v0 offset0:66 offset1:99
	ds_read2_b32 v[50:51], v0 offset0:132 offset1:165
	ds_read2_b32 v[52:53], v0 offset0:198 offset1:231
	v_or_b32_e32 v0, s5, v12
	v_lshlrev_b32_e32 v0, 11, v0
	s_waitcnt lgkmcnt(0)
	v_cvt_pk_bf16_f32 v6, v6, v7
	v_cvt_pk_bf16_f32 v7, v8, v9
	v_cvt_pk_bf16_f32 v8, v50, v51
	v_cvt_pk_bf16_f32 v9, v52, v53
	v_lshl_add_u64 v[50:51], v[56:57], 0, v[0:1]
	flat_store_dwordx4 v[50:51], v[6:9]
	v_add_u32_e32 v0, s27, v15
	ds_read2_b32 v[6:7], v0 offset1:33
	ds_read2_b32 v[8:9], v0 offset0:66 offset1:99
	ds_read2_b32 v[50:51], v0 offset0:132 offset1:165
	ds_read2_b32 v[52:53], v0 offset0:198 offset1:231
	v_or_b32_e32 v0, s5, v14
	v_lshlrev_b32_e32 v0, 11, v0
	s_waitcnt lgkmcnt(0)
	v_cvt_pk_bf16_f32 v6, v6, v7
	v_cvt_pk_bf16_f32 v7, v8, v9
	v_cvt_pk_bf16_f32 v8, v50, v51
	v_cvt_pk_bf16_f32 v9, v52, v53
	v_lshl_add_u64 v[50:51], v[56:57], 0, v[0:1]
	flat_store_dwordx4 v[50:51], v[6:9]
	v_add_u32_e32 v0, s27, v17
	ds_read2_b32 v[6:7], v0 offset1:33
	ds_read2_b32 v[8:9], v0 offset0:66 offset1:99
	ds_read2_b32 v[50:51], v0 offset0:132 offset1:165
	ds_read2_b32 v[52:53], v0 offset0:198 offset1:231
	v_or_b32_e32 v0, s5, v16
	v_lshlrev_b32_e32 v0, 11, v0
	s_waitcnt lgkmcnt(0)
	v_cvt_pk_bf16_f32 v6, v6, v7
	v_cvt_pk_bf16_f32 v7, v8, v9
	v_cvt_pk_bf16_f32 v8, v50, v51
	v_cvt_pk_bf16_f32 v9, v52, v53
	v_lshl_add_u64 v[50:51], v[56:57], 0, v[0:1]
	flat_store_dwordx4 v[50:51], v[6:9]
	s_waitcnt lgkmcnt(0)

.LBB0_873:
	s_lshl_b32 s2, s4, 10
	s_ashr_i32 s3, s2, 31
	s_lshl_b64 s[2:3], s[2:3], 2
	s_waitcnt lgkmcnt(0)
	s_add_u32 s4, s24, s2
	s_addc_u32 s7, s25, s3
	s_ashr_i32 s21, s20, 31
	s_lshl_b64 s[2:3], s[20:21], 2
	s_add_u32 s6, s4, s2
	s_addc_u32 s7, s7, s3
	v_lshlrev_b32_e32 v0, 2, v2
	s_cmp_lg_u64 s[24:25], 0
	s_cselect_b64 s[2:3], -1, 0
	s_cmp_eq_u64 s[24:25], 0
	v_lshl_add_u64 v[6:7], s[6:7], 0, v[0:1]
	s_cbranch_scc1 .LBB0_875
	global_load_dword v96, v[6:7], off offset:0
	global_load_dword v97, v[6:7], off offset:8
	global_load_dword v98, v[6:7], off offset:16
	global_load_dword v99, v[6:7], off offset:24
	global_load_dword v100, v[6:7], off offset:32
	global_load_dword v101, v[6:7], off offset:40
	global_load_dword v102, v[6:7], off offset:48
	global_load_dword v103, v[6:7], off offset:56
	global_load_dword v104, v[6:7], off offset:64
	global_load_dword v105, v[6:7], off offset:72
	global_load_dword v106, v[6:7], off offset:80
	global_load_dword v107, v[6:7], off offset:88
	global_load_dword v108, v[6:7], off offset:96
	global_load_dword v109, v[6:7], off offset:104
	global_load_dword v110, v[6:7], off offset:112
	global_load_dword v111, v[6:7], off offset:120
	global_load_dword v112, v[6:7], off offset:128
	global_load_dword v113, v[6:7], off offset:136
	global_load_dword v114, v[6:7], off offset:144
	global_load_dword v115, v[6:7], off offset:152
	global_load_dword v116, v[6:7], off offset:160
	global_load_dword v117, v[6:7], off offset:168
	global_load_dword v118, v[6:7], off offset:176
	global_load_dword v119, v[6:7], off offset:184
	global_load_dword v120, v[6:7], off offset:192
	global_load_dword v121, v[6:7], off offset:200
	global_load_dword v122, v[6:7], off offset:208
	global_load_dword v123, v[6:7], off offset:216
	global_load_dword v124, v[6:7], off offset:224
	global_load_dword v125, v[6:7], off offset:232
	global_load_dword v126, v[6:7], off offset:240
	global_load_dword v127, v[6:7], off offset:248
	s_branch .LBB0_876

.LBB0_876:
	v_cndmask_b32_e64 v9, 0, 1, s[2:3]
	s_waitcnt vmcnt(0)
	v_mul_f32_e32 v8, v50, v96
	v_cmp_ne_u32_e64 s[38:39], 1, v9
	s_andn2_b64 vcc, exec, s[2:3]
	ds_write_b32 v5, v8
	s_cbranch_vccnz .LBB0_878
	s_nop 0
.LBB0_878:
	s_waitcnt vmcnt(0)
	v_mul_f32_e32 v8, v49, v97
	v_add_u32_e32 v9, s27, v18
	s_and_b64 vcc, exec, s[38:39]
	ds_write_b32 v9, v8
	s_cbranch_vccnz .LBB0_880
	s_nop 0
.LBB0_880:
	s_waitcnt vmcnt(0)
	v_mul_f32_e32 v8, v53, v98
	v_add_u32_e32 v9, s27, v19
	s_and_b64 vcc, exec, s[38:39]
	ds_write_b32 v9, v8
	s_cbranch_vccnz .LBB0_882
	s_nop 0
.LBB0_882:
	s_waitcnt vmcnt(0)
	v_mul_f32_e32 v8, v51, v99
	v_add_u32_e32 v9, s27, v20
	s_and_b64 vcc, exec, s[38:39]
	ds_write_b32 v9, v8
	s_cbranch_vccnz .LBB0_884
	s_nop 0
.LBB0_884:
	s_waitcnt vmcnt(0)
	v_mul_f32_e32 v8, v55, v100
	v_add_u32_e32 v9, s27, v21
	s_and_b64 vcc, exec, s[38:39]
	ds_write_b32 v9, v8
	s_cbranch_vccnz .LBB0_886
	s_nop 0
.LBB0_886:
	s_waitcnt vmcnt(0)
	v_mul_f32_e32 v8, v52, v101
	v_add_u32_e32 v9, s27, v22
	s_and_b64 vcc, exec, s[38:39]
	ds_write_b32 v9, v8
	s_cbranch_vccnz .LBB0_888
	s_nop 0
.LBB0_888:
	s_waitcnt vmcnt(0)
	v_mul_f32_e32 v8, v57, v102
	v_add_u32_e32 v9, s27, v23
	s_and_b64 vcc, exec, s[38:39]
	ds_write_b32 v9, v8
	s_cbranch_vccnz .LBB0_890
	s_nop 0
.LBB0_890:
	s_waitcnt vmcnt(0)
	v_mul_f32_e32 v8, v54, v103
	v_add_u32_e32 v9, s27, v24
	s_and_b64 vcc, exec, s[38:39]
	ds_write_b32 v9, v8
	s_cbranch_vccnz .LBB0_892
	s_nop 0
.LBB0_892:
	s_waitcnt vmcnt(0)
	v_mul_f32_e32 v8, v59, v104
	v_add_u32_e32 v9, s27, v25
	s_and_b64 vcc, exec, s[38:39]
	ds_write_b32 v9, v8
	s_cbranch_vccnz .LBB0_894
	s_nop 0
.LBB0_894:
	s_waitcnt vmcnt(0)
	v_mul_f32_e32 v8, v56, v105
	v_add_u32_e32 v9, s27, v26
	s_and_b64 vcc, exec, s[38:39]
	ds_write_b32 v9, v8
	s_cbranch_vccnz .LBB0_896
	s_nop 0
.LBB0_896:
	s_waitcnt vmcnt(0)
	v_mul_f32_e32 v8, v61, v106
	v_add_u32_e32 v9, s27, v27
	s_and_b64 vcc, exec, s[38:39]
	ds_write_b32 v9, v8
	s_cbranch_vccnz .LBB0_898
	s_nop 0
.LBB0_898:
	s_waitcnt vmcnt(0)
	v_mul_f32_e32 v8, v58, v107
	v_add_u32_e32 v9, s27, v28
	s_and_b64 vcc, exec, s[38:39]
	ds_write_b32 v9, v8
	s_cbranch_vccnz .LBB0_900
	s_nop 0
.LBB0_900:
	s_waitcnt vmcnt(0)
	v_mul_f32_e32 v8, v63, v108
	v_add_u32_e32 v9, s27, v29
	s_and_b64 vcc, exec, s[38:39]
	ds_write_b32 v9, v8
	s_cbranch_vccnz .LBB0_902
	s_nop 0
.LBB0_902:
	s_waitcnt vmcnt(0)
	v_mul_f32_e32 v8, v60, v109
	v_add_u32_e32 v9, s27, v30
	s_and_b64 vcc, exec, s[38:39]
	ds_write_b32 v9, v8
	s_cbranch_vccnz .LBB0_904
	s_nop 0
.LBB0_904:
	s_waitcnt vmcnt(0)
	v_mul_f32_e32 v8, v65, v110
	v_add_u32_e32 v9, s27, v31
	s_and_b64 vcc, exec, s[38:39]
	ds_write_b32 v9, v8
	s_cbranch_vccnz .LBB0_906
	s_nop 0
.LBB0_906:
	s_waitcnt vmcnt(0)
	v_mul_f32_e32 v8, v62, v111
	v_add_u32_e32 v9, s27, v32
	s_and_b64 vcc, exec, s[38:39]
	ds_write_b32 v9, v8
	s_cbranch_vccnz .LBB0_908
	s_nop 0
.LBB0_908:
	s_waitcnt vmcnt(0)
	v_mul_f32_e32 v8, v67, v112
	v_add_u32_e32 v9, s27, v33
	s_and_b64 vcc, exec, s[38:39]
	ds_write_b32 v9, v8
	s_cbranch_vccnz .LBB0_910
	s_nop 0
.LBB0_910:
	s_waitcnt vmcnt(0)
	v_mul_f32_e32 v8, v64, v113
	v_add_u32_e32 v9, s27, v34
	s_and_b64 vcc, exec, s[38:39]
	ds_write_b32 v9, v8
	s_cbranch_vccnz .LBB0_912
	s_nop 0
.LBB0_912:
	s_waitcnt vmcnt(0)
	v_mul_f32_e32 v8, v69, v114
	v_add_u32_e32 v9, s27, v35
	s_and_b64 vcc, exec, s[38:39]
	ds_write_b32 v9, v8
	s_cbranch_vccnz .LBB0_914
	s_nop 0
.LBB0_914:
	s_waitcnt vmcnt(0)
	v_mul_f32_e32 v8, v66, v115
	v_add_u32_e32 v9, s27, v36
	s_and_b64 vcc, exec, s[38:39]
	ds_write_b32 v9, v8
	s_cbranch_vccnz .LBB0_916
	s_nop 0
.LBB0_916:
	s_waitcnt vmcnt(0)
	v_mul_f32_e32 v8, v71, v116
	v_add_u32_e32 v9, s27, v37
	s_and_b64 vcc, exec, s[38:39]
	ds_write_b32 v9, v8
	s_cbranch_vccnz .LBB0_918
	s_nop 0
.LBB0_918:
	s_waitcnt vmcnt(0)
	v_mul_f32_e32 v8, v68, v117
	v_add_u32_e32 v9, s27, v38
	s_and_b64 vcc, exec, s[38:39]
	ds_write_b32 v9, v8
	s_cbranch_vccnz .LBB0_920
	s_nop 0
.LBB0_920:
	s_waitcnt vmcnt(0)
	v_mul_f32_e32 v8, v73, v118
	v_add_u32_e32 v9, s27, v39
	s_and_b64 vcc, exec, s[38:39]
	ds_write_b32 v9, v8
	s_cbranch_vccnz .LBB0_922
	s_nop 0
.LBB0_922:
	s_waitcnt vmcnt(0)
	v_mul_f32_e32 v8, v70, v119
	v_add_u32_e32 v9, s27, v40
	s_and_b64 vcc, exec, s[38:39]
	ds_write_b32 v9, v8
	s_cbranch_vccnz .LBB0_924
	s_nop 0
.LBB0_924:
	s_waitcnt vmcnt(0)
	v_mul_f32_e32 v8, v75, v120
	v_add_u32_e32 v9, s27, v41
	s_and_b64 vcc, exec, s[38:39]
	ds_write_b32 v9, v8
	s_cbranch_vccnz .LBB0_926
	s_nop 0
.LBB0_926:
	s_waitcnt vmcnt(0)
	v_mul_f32_e32 v8, v72, v121
	v_add_u32_e32 v9, s27, v42
	s_and_b64 vcc, exec, s[38:39]
	ds_write_b32 v9, v8
	s_cbranch_vccnz .LBB0_928
	s_nop 0
.LBB0_928:
	s_waitcnt vmcnt(0)
	v_mul_f32_e32 v8, v77, v122
	v_add_u32_e32 v9, s27, v43
	s_and_b64 vcc, exec, s[38:39]
	ds_write_b32 v9, v8
	s_cbranch_vccnz .LBB0_930
	s_nop 0
.LBB0_930:
	s_waitcnt vmcnt(0)
	v_mul_f32_e32 v8, v74, v123
	v_add_u32_e32 v9, s27, v44
	s_and_b64 vcc, exec, s[38:39]
	ds_write_b32 v9, v8
	s_cbranch_vccnz .LBB0_932
	s_nop 0
.LBB0_932:
	s_waitcnt vmcnt(0)
	v_mul_f32_e32 v8, v79, v124
	v_add_u32_e32 v9, s27, v45
	s_and_b64 vcc, exec, s[38:39]
	ds_write_b32 v9, v8
	s_cbranch_vccnz .LBB0_934
	s_nop 0
.LBB0_934:
	s_waitcnt vmcnt(0)
	v_mul_f32_e32 v8, v76, v125
	v_add_u32_e32 v9, s27, v46
	s_and_b64 vcc, exec, s[38:39]
	ds_write_b32 v9, v8
	s_cbranch_vccnz .LBB0_936
	s_nop 0
.LBB0_936:
	s_waitcnt vmcnt(0)
	v_mul_f32_e32 v8, v80, v126
	v_add_u32_e32 v9, s27, v47
	s_and_b64 vcc, exec, s[38:39]
	ds_write_b32 v9, v8
	s_cbranch_vccnz .LBB0_572
	s_nop 0
	s_branch .LBB0_572
